# MIX1 queue order in cycles of 9 LRU + 4 sample HGRN + 24 attention items after one HGRN pass-1 item per workgroup
# speedup vs baseline: 1.0049x; 1.0024x over previous
.LBB0_510:
	s_andn2_b64 vcc, exec, s[2:3]
	s_cbranch_vccnz .LBB0_1032
	v_readlane_b32 s2, v254, 55
	s_cmp_gt_i32 s2, 0
	s_mov_b64 s[2:3], -1
	s_cbranch_scc0 .LBB0_791
	v_readlane_b32 s2, v251, 56
	v_readlane_b32 s3, v251, 57
	s_andn2_b64 vcc, exec, s[2:3]
	s_cbranch_vccnz .LBB0_790
	v_readlane_b32 s12, v254, 51
	v_readlane_b32 s13, v254, 52
	s_and_b64 s[2:3], s[12:13], exec
	s_movk_i32 s2, 0x200
	s_cselect_b32 s2, s2, 0x100
	s_add_u32 s2, s8, s2
	s_addc_u32 s3, s9, 0
	v_writelane_b32 v254, s2, 58
	v_readlane_b32 s44, v252, 4
	v_readlane_b32 s58, v252, 18
	v_writelane_b32 v254, s3, 59
	s_add_u32 s2, s8, 0x36900000
	s_addc_u32 s3, s9, 0
	v_writelane_b32 v254, s2, 60
	v_readlane_b32 s59, v252, 19
	v_readlane_b32 s24, v253, 58
	v_writelane_b32 v254, s3, 61
	s_add_u32 s2, s8, 0x38200000
	s_addc_u32 s3, s9, 0
	v_writelane_b32 v254, s2, 62
	s_add_u32 s83, s8, 0x17000400
	v_readlane_b32 s28, v253, 62
	v_writelane_b32 v254, s3, 63
	s_addc_u32 s2, s9, 0
	v_writelane_b32 v255, s2, 0
	s_add_u32 s2, s8, 0x38400000
	v_writelane_b32 v255, s2, 1
	s_addc_u32 s2, s9, 0
	v_writelane_b32 v255, s2, 2
	s_add_u32 s2, s8, 0x3a400000
	v_writelane_b32 v255, s2, 3
	s_addc_u32 s2, s9, 0
	v_writelane_b32 v255, s2, 4
	s_and_b64 s[2:3], s[12:13], exec
	s_cselect_b32 s2, 0x2000, 0
	s_add_u32 s2, s58, s2
	s_addc_u32 s3, s59, 0
	v_writelane_b32 v255, s2, 5
	v_readlane_b32 s29, v253, 63
	v_readlane_b32 s45, v252, 5
	v_writelane_b32 v255, s3, 6
	s_and_b64 s[2:3], s[12:13], exec
	s_cselect_b32 s2, 32, 0
	v_writelane_b32 v255, s2, 7
	s_cselect_b32 s2, 0x20000, 0
	s_cselect_b32 s95, 0x200, 0
	s_add_u32 s2, s8, s2
	s_addc_u32 s3, s9, 0
	s_add_u32 s22, s2, 0x36800000
	s_addc_u32 s23, s3, 0
	s_and_b64 s[2:3], s[12:13], exec
	s_cselect_b32 s2, 0x10000, 0
	s_add_u32 s3, s42, s2
	v_writelane_b32 v255, s3, 9
	s_addc_u32 s3, s43, 0
	v_writelane_b32 v255, s3, 11
	s_add_u32 s2, s28, s2
	v_writelane_b32 v255, s2, 13
	s_addc_u32 s2, s29, 0
	v_writelane_b32 v255, s2, 14
	s_and_b64 s[2:3], s[12:13], exec
	s_cselect_b32 s2, 0x1800, 0
	v_readlane_b32 s3, v251, 62
	s_add_u32 s12, s3, s2
	v_readlane_b32 s2, v251, 63
	s_addc_u32 s13, s2, 0
	s_add_u32 s34, s8, 0x3df00000
	v_writelane_b32 v255, s12, 15
	s_addc_u32 s35, s9, 0
	s_add_u32 s2, s8, 0x36600000
	v_writelane_b32 v255, s13, 16
	v_writelane_b32 v255, s2, 17
	s_addc_u32 s2, s9, 0
	v_writelane_b32 v255, s2, 18
	v_readlane_b32 s2, v254, 3
	v_readlane_b32 s46, v252, 6
	v_readlane_b32 s47, v252, 7
	v_readlane_b32 s48, v252, 8
	v_readlane_b32 s49, v252, 9
	v_readlane_b32 s50, v252, 10
	v_readlane_b32 s51, v252, 11
	v_readlane_b32 s52, v252, 12
	v_readlane_b32 s53, v252, 13
	v_readlane_b32 s54, v252, 14
	v_readlane_b32 s55, v252, 15
	v_readlane_b32 s56, v252, 16
	v_readlane_b32 s57, v252, 17
	v_readlane_b32 s25, v253, 59
	v_readlane_b32 s26, v253, 60
	v_readlane_b32 s27, v253, 61
	v_readlane_b32 s30, v254, 0
	v_readlane_b32 s31, v254, 1
	v_readlane_b32 s3, v254, 4
	v_readlane_b32 s14, v251, 8
	s_cmp_lg_u32 s14, 0
	s_cselect_b32 s14, 0x120, 0
	s_add_i32 s2, s2, s14
	s_branch .LBB0_516
.LBB0_514:
	s_or_b64 exec, exec, s[24:25]
	s_waitcnt vmcnt(0)
	v_readfirstlane_b32 s14, v2
	v_readlane_b32 s12, v251, 8
	s_cmp_lg_u32 s12, 0
	s_cbranch_scc1 .Lq_map
	s_add_i32 s14, s92, s14
	s_branch .Lq_mapped
.Lq_map:
	s_cmpk_ge_u32 s14, 0x4a0
	s_cbranch_scc1 .Lq_end
	s_mul_hi_u32 s12, s14, 0x6eb3e46
	s_mul_i32 s13, s12, 37
	s_sub_i32 s13, s14, s13
	s_cmpk_ge_u32 s13, 9
	s_cbranch_scc1 .Lq_k2
	s_mul_i32 s14, s12, 9
	s_add_i32 s14, s14, s13
	s_branch .Lq_mapped
.Lq_k2:
	s_cmpk_ge_u32 s13, 13
	s_cbranch_scc1 .Lq_k3
	s_lshl_b32 s14, s12, 2
	s_add_i32 s14, s14, s13
	s_addk_i32 s14, 0x217
	s_branch .Lq_mapped
.Lq_k3:
	s_mul_i32 s14, s12, 24
	s_add_i32 s14, s14, s13
	s_addk_i32 s14, 0x293
	s_branch .Lq_mapped
.Lq_end:
	s_movk_i32 s14, 0x5a0
.Lq_mapped:
	v_readlane_b32 s12, v254, 11
	v_add_u32_e32 v0, s14, v0
	s_nop 0
	v_mov_b32_e32 v2, s12
	ds_write_b32 v2, v0
